# key-norm table counter requested together with the pre-pass loads (one memory round trip less per FoX unit)
# baseline (speedup 1.0000x reference)
.LBB0_574:
	s_sub_u32 s2, s26, s10
	s_lshr_b32 s2, s2, 14
	s_lshl_b32 s2, s2, 6
	s_lshl_b32 s3, s16, 11
	s_add_i32 s2, s2, s3
	s_getpc_b64 s[100:101]
	s_add_u32 s100, s100, g_ctl@rel32@lo+51204
	s_addc_u32 s101, s101, g_ctl@rel32@hi+51212
	s_add_u32 s100, s100, s2
	s_addc_u32 s101, s101, 0
	v_readfirstlane_b32 s2, v165
	s_nop 3
	s_lshr_b32 s2, s2, 6
	s_lshl_b32 s2, s2, 5
	s_lshl_b32 s3, s48, 8
	s_add_i32 s2, s2, s3
	s_add_i32 s20, s2, -32
	s_lshl_b32 s42, s20, 2
	s_mul_i32 s20, s20, 0x1e00
	s_add_u32 s20, s20, 0x7001200
	s_add_u32 s2, s28, s20
	s_addc_u32 s3, s29, 0
	v_and_b32_e32 v60, 31, v165
	v_mul_u32_u24_e32 v60, 0x1e00, v60
	v_bfe_u32 v61, v165, 5, 1
	v_lshl_add_u32 v60, v61, 4, v60
	v_add_u32_e32 v61, s42, v179
	global_load_dwordx4 v[64:67], v60, s[2:3] offset:0
	global_load_dwordx4 v[68:71], v60, s[2:3] offset:32
	global_load_dwordx4 v[72:75], v60, s[2:3] offset:64
	global_load_dwordx4 v[76:79], v60, s[2:3] offset:96
	global_load_dword v210, v191, s[100:101] offset:32 sc1
	ds_read_b128 v[32:35], v61
	ds_read_b128 v[36:39], v61 offset:32
	ds_read_b128 v[40:43], v61 offset:64
	ds_read_b128 v[44:47], v61 offset:96
	s_waitcnt lgkmcnt(0)
	s_waitcnt vmcnt(4)
	v_mfma_f32_32x32x16_bf16 v[32:47], v[64:67], v[96:99], v[32:47]
	s_waitcnt vmcnt(3)
	v_mfma_f32_32x32x16_bf16 v[32:47], v[68:71], v[100:103], v[32:47]
	s_waitcnt vmcnt(2)
	v_mfma_f32_32x32x16_bf16 v[32:47], v[72:75], v[104:107], v[32:47]
	s_waitcnt vmcnt(1)
	v_mfma_f32_32x32x16_bf16 v[32:47], v[76:79], v[108:111], v[32:47]
	s_nop 11
	v_max3_f32 v222, v32, v33, v34
	v_max3_f32 v222, v222, v35, v36
	v_max3_f32 v222, v222, v37, v38
	v_max3_f32 v222, v222, v39, v40
	v_max3_f32 v222, v222, v41, v42
	v_max3_f32 v222, v222, v43, v44
	v_max3_f32 v222, v222, v45, v46
	v_max_f32_e32 v222, v222, v47
	ds_bpermute_b32 v183, v180, v222
	s_waitcnt lgkmcnt(0)
	v_max_f32_e32 v183, v183, v183
	v_max_f32_e32 v182, v222, v183
	v_sub_f32_e32 v182, v182, v161
	v_add_f32_e32 v255, 0xc2200000, v182
	s_waitcnt vmcnt(0)
	v_readfirstlane_b32 s2, v210
	s_nop 3
	s_cmp_ge_u32 s2, 64
	s_cbranch_scc1 .Lfox_km_ready
	s_mov_b32 s20, 0
